# v14 plus layer-0 GEMM2 f32 residual loads without the non-temporal hint (rows were read in prologue B: served from cache)
# baseline (speedup 1.0000x reference)
.LBB0_401:
	s_lshl_b64 s[42:43], s[26:27], 2
	s_add_u32 s40, s40, s42
	s_addc_u32 s41, s41, s43
	v_lshlrev_b32_e32 v80, 2, v157
	v_lshl_add_u64 v[48:49], s[40:41], 0, v[80:81]
	v_lshlrev_b64 v[50:51], 12, v[140:141]
	v_lshl_add_u64 v[48:49], v[48:49], 0, v[50:51]
	s_mov_b32 s0, 0x8000
	v_add_co_u32_e32 v52, vcc, s0, v48
	s_mov_b64 s[40:41], 0x8000
	s_nop 0
	v_addc_co_u32_e32 v53, vcc, 0, v49, vcc
	global_load_dwordx4 v[110:113], v[48:49], off
	global_load_dwordx4 v[106:109], v[48:49], off offset:16
	v_lshl_add_u64 v[50:51], v[48:49], 0, s[40:41]
	global_load_dwordx4 v[102:105], v[52:53], off
	global_load_dwordx4 v[98:101], v[50:51], off offset:16
	s_mov_b64 s[40:41], 0x10000
	v_add_co_u32_e32 v52, vcc, 0x10000, v48
	v_lshl_add_u64 v[50:51], v[48:49], 0, s[40:41]
	s_nop 0
	v_addc_co_u32_e32 v53, vcc, 0, v49, vcc
	global_load_dwordx4 v[60:63], v[52:53], off
	global_load_dwordx4 v[56:59], v[50:51], off offset:16
	v_lshl_add_u64 v[50:51], v[48:49], 0, s[70:71]
	v_add_co_u32_e32 v48, vcc, 0x18000, v48
	v_lshlrev_b64 v[146:147], 11, v[140:141]
	s_nop 0
	v_addc_co_u32_e32 v49, vcc, 0, v49, vcc
	global_load_dwordx4 v[52:55], v[48:49], off
	s_nop 0
	global_load_dwordx4 v[48:51], v[50:51], off offset:16

.LBB0_441:
	s_lshl_b64 s[26:27], s[26:27], 2
	s_add_u32 s16, s16, s26
	s_addc_u32 s17, s17, s27
	v_lshlrev_b32_e32 v80, 2, v157
	v_lshl_add_u64 v[48:49], s[16:17], 0, v[80:81]
	s_waitcnt lgkmcnt(0)
	v_lshlrev_b64 v[50:51], 12, v[140:141]
	v_lshl_add_u64 v[50:51], v[48:49], 0, v[50:51]
	global_load_dwordx4 v[76:79], v[50:51], off
	global_load_dwordx4 v[72:75], v[50:51], off offset:16
	v_lshlrev_b64 v[50:51], 12, v[84:85]
	v_lshl_add_u64 v[50:51], v[48:49], 0, v[50:51]
	global_load_dwordx4 v[68:71], v[50:51], off
	global_load_dwordx4 v[64:67], v[50:51], off offset:16
	v_lshlrev_b64 v[50:51], 12, v[86:87]
	v_lshl_add_u64 v[50:51], v[48:49], 0, v[50:51]
	global_load_dwordx4 v[60:63], v[50:51], off
	global_load_dwordx4 v[56:59], v[50:51], off offset:16
	v_lshlrev_b64 v[50:51], 12, v[88:89]
	v_lshl_add_u64 v[48:49], v[48:49], 0, v[50:51]
	global_load_dwordx4 v[52:55], v[48:49], off
	s_nop 0
	global_load_dwordx4 v[48:51], v[48:49], off offset:16
